# vp56 plus nop padding in the P8 K-loop load segments so each post-barrier MFMA block starts on a 64-byte line
# baseline (speedup 1.0000x reference)
; template <class Epi, class Sched, bool ALIGN_EPI = false, bool SP2 = false, bool FP8 = false, bool MIX8 = false>
; __device__ __forceinline__ void gemm_phase(PG8_LAS unsigned char* lds, const Gemm g, const Sched& S, const Epi& E) {
;     ...
;             const bool last = (t == nt - 2);
;             if constexpr (Epi::MID_HOOK) { if (t == E.mid_t(nt)) { if constexpr (FP8) asm volatile("s_nop 15\n\ts_nop 15\n\ts_nop 15" ::: "memory");
;                 E.mid(acc, cur, wr, wc, fr, fq); } }
;             const char* a1 = cA + (size_t)(t + 1) * kstep;
;             const char* a2 = last ? nA : cA + (size_t)(t + 2) * kstep; const char* b2 = last ? nB : cB + (size_t)(t + 2) * kstep;
;             const char* a3 = a2 + kstep; const char* b3 = b2 + kstep;
.LBB0_723:
	ds_read_b128 v[154:157], v149
	ds_read_b128 v[158:161], v149 offset:1024
	ds_read_b128 v[162:165], v149 offset:2048
	ds_read_b128 v[166:169], v149 offset:3072
	ds_read_b128 v[170:173], v150
	ds_read_b128 v[174:177], v150 offset:1024
	ds_read_b128 v[178:181], v150 offset:2048
	ds_read_b128 v[182:185], v150 offset:3072
	s_add_u32 s30, s28, 0xfff80080
	s_addc_u32 s31, s29, -1
	s_cmp_eq_u32 s59, 28
	s_cselect_b32 s35, s1, s31
	s_cselect_b32 s34, s9, s30
	s_cselect_b32 s31, s19, s33
	s_cselect_b32 s30, s21, s27
	v_lshl_add_u64 v[144:145], s[28:29], 0, v[136:137]
	s_add_i32 m0, s47, 0xc000
	ds_read_b128 v[186:189], v151
	ds_read_b128 v[190:193], v151 offset:1024
	ds_read_b128 v[194:197], v151 offset:2048
	ds_read_b128 v[198:201], v151 offset:3072
	ds_read_b128 v[202:205], v151 offset:4096
	ds_read_b128 v[206:209], v151 offset:5120
	ds_read_b128 v[210:213], v151 offset:6144
	ds_read_b128 v[214:217], v151 offset:7168
	global_load_lds_dwordx4 v[144:145], off
	v_lshl_add_u64 v[144:145], s[28:29], 0, v[138:139]
	s_add_i32 m0, s47, 0xe000
	s_nop 0
	global_load_lds_dwordx4 v[144:145], off
	s_nop 0
	s_nop 0
	s_nop 0
	s_nop 0
	s_nop 0
	s_nop 0
	s_nop 0
	s_nop 0
	s_nop 0
	s_nop 0
	s_nop 0
	s_nop 0
	s_nop 0
	s_waitcnt vmcnt(8)
	s_waitcnt lgkmcnt(0)
	s_barrier
	s_setprio 1
	s_waitcnt lgkmcnt(0)
	v_mfma_f32_16x16x32_bf16 v[124:127], v[154:157], v[186:189], v[124:127]
	v_mfma_f32_16x16x32_bf16 v[120:123], v[162:165], v[186:189], v[120:123]
	v_mfma_f32_16x16x32_bf16 v[108:111], v[154:157], v[194:197], v[108:111]
	v_mfma_f32_16x16x32_bf16 v[104:107], v[162:165], v[194:197], v[104:107]
	v_mfma_f32_16x16x32_bf16 v[92:95], v[154:157], v[202:205], v[92:95]
	v_mfma_f32_16x16x32_bf16 v[88:91], v[162:165], v[202:205], v[88:91]
	v_mfma_f32_16x16x32_bf16 v[76:79], v[154:157], v[210:213], v[76:79]
	v_mfma_f32_16x16x32_bf16 v[72:75], v[162:165], v[210:213], v[72:75]
	v_mfma_f32_16x16x32_bf16 v[124:127], v[158:161], v[190:193], v[124:127]
	v_mfma_f32_16x16x32_bf16 v[120:123], v[166:169], v[190:193], v[120:123]
	v_mfma_f32_16x16x32_bf16 v[108:111], v[158:161], v[198:201], v[108:111]
	v_mfma_f32_16x16x32_bf16 v[104:107], v[166:169], v[198:201], v[104:107]
	v_mfma_f32_16x16x32_bf16 v[92:95], v[158:161], v[206:209], v[92:95]
	v_mfma_f32_16x16x32_bf16 v[88:91], v[166:169], v[206:209], v[88:91]
	v_mfma_f32_16x16x32_bf16 v[76:79], v[158:161], v[214:217], v[76:79]
	v_mfma_f32_16x16x32_bf16 v[72:75], v[166:169], v[214:217], v[72:75]
	s_setprio 0
	s_setprio 1
	v_mfma_f32_16x16x32_bf16 v[116:119], v[170:173], v[186:189], v[116:119]
	v_mfma_f32_16x16x32_bf16 v[112:115], v[178:181], v[186:189], v[112:115]
	v_mfma_f32_16x16x32_bf16 v[100:103], v[170:173], v[194:197], v[100:103]
	v_mfma_f32_16x16x32_bf16 v[96:99], v[178:181], v[194:197], v[96:99]
	v_mfma_f32_16x16x32_bf16 v[84:87], v[170:173], v[202:205], v[84:87]
	v_mfma_f32_16x16x32_bf16 v[80:83], v[178:181], v[202:205], v[80:83]
	v_mfma_f32_16x16x32_bf16 v[68:71], v[170:173], v[210:213], v[68:71]
	v_mfma_f32_16x16x32_bf16 v[64:67], v[178:181], v[210:213], v[64:67]
	v_mfma_f32_16x16x32_bf16 v[116:119], v[174:177], v[190:193], v[116:119]
	v_mfma_f32_16x16x32_bf16 v[112:115], v[182:185], v[190:193], v[112:115]
	v_mfma_f32_16x16x32_bf16 v[100:103], v[174:177], v[198:201], v[100:103]
	v_mfma_f32_16x16x32_bf16 v[96:99], v[182:185], v[198:201], v[96:99]
	v_mfma_f32_16x16x32_bf16 v[84:87], v[174:177], v[206:209], v[84:87]
	v_mfma_f32_16x16x32_bf16 v[80:83], v[182:185], v[206:209], v[80:83]
	v_mfma_f32_16x16x32_bf16 v[68:71], v[174:177], v[214:217], v[68:71]
	v_mfma_f32_16x16x32_bf16 v[64:67], v[182:185], v[214:217], v[64:67]
	s_setprio 0
	s_barrier
	s_add_i32 s60, s56, s46
	v_lshl_add_u64 v[144:145], s[30:31], 0, v[130:131]
	s_mov_b32 m0, s60
	ds_read_b128 v[186:189], v151 offset:16384
	ds_read_b128 v[190:193], v151 offset:17408
	ds_read_b128 v[194:197], v151 offset:18432
	ds_read_b128 v[198:201], v151 offset:19456
	ds_read_b128 v[202:205], v151 offset:20480
	ds_read_b128 v[206:209], v151 offset:21504
	ds_read_b128 v[210:213], v151 offset:22528
	ds_read_b128 v[214:217], v151 offset:23552
	global_load_lds_dwordx4 v[144:145], off
	s_add_i32 m0, s60, 0x2000
	s_add_u32 s60, s30, 0x80000
	v_lshl_add_u64 v[218:219], s[30:31], 0, v[134:135]
	s_addc_u32 s61, s31, 0
	s_add_i32 s62, s57, s46
	global_load_lds_dwordx4 v[218:219], off
	v_lshl_add_u64 v[220:221], s[60:61], 0, v[130:131]
	s_mov_b32 m0, s62
	v_lshl_add_u64 v[222:223], s[34:35], 0, v[132:133]
	global_load_lds_dwordx4 v[220:221], off
	v_lshl_add_u64 v[220:221], s[60:61], 0, v[134:135]
	s_add_i32 m0, s62, 0x2000
	s_nop 0
	global_load_lds_dwordx4 v[220:221], off
	v_lshl_add_u64 v[220:221], s[34:35], 0, v[128:129]
	s_mov_b32 m0, s47
	s_nop 0
	global_load_lds_dwordx4 v[220:221], off
	s_mov_b32 m0, s36
	s_nop 0
	global_load_lds_dwordx4 v[222:223], off
	s_nop 0
	s_nop 0
	s_nop 0
	s_nop 0
	s_nop 0
	s_nop 0
	s_nop 0
	s_nop 0
	s_nop 0
	s_nop 0
	s_nop 0
	s_nop 0
	s_nop 0
	s_nop 0
	s_nop 0
	s_waitcnt vmcnt(8)
	s_waitcnt lgkmcnt(0)
	s_barrier
	s_setprio 1
	s_waitcnt lgkmcnt(0)
	v_mfma_f32_16x16x32_bf16 v[60:63], v[154:157], v[186:189], v[60:63]
	v_mfma_f32_16x16x32_bf16 v[56:59], v[162:165], v[186:189], v[56:59]
	v_mfma_f32_16x16x32_bf16 v[44:47], v[154:157], v[194:197], v[44:47]
	v_mfma_f32_16x16x32_bf16 v[40:43], v[162:165], v[194:197], v[40:43]
	v_mfma_f32_16x16x32_bf16 v[28:31], v[154:157], v[202:205], v[28:31]
	v_mfma_f32_16x16x32_bf16 v[24:27], v[162:165], v[202:205], v[24:27]
	v_mfma_f32_16x16x32_bf16 v[12:15], v[154:157], v[210:213], v[12:15]
	v_mfma_f32_16x16x32_bf16 v[8:11], v[162:165], v[210:213], v[8:11]
	v_mfma_f32_16x16x32_bf16 v[60:63], v[158:161], v[190:193], v[60:63]
	v_mfma_f32_16x16x32_bf16 v[56:59], v[166:169], v[190:193], v[56:59]
	v_mfma_f32_16x16x32_bf16 v[44:47], v[158:161], v[198:201], v[44:47]
	v_mfma_f32_16x16x32_bf16 v[40:43], v[166:169], v[198:201], v[40:43]
	v_mfma_f32_16x16x32_bf16 v[28:31], v[158:161], v[206:209], v[28:31]
	v_mfma_f32_16x16x32_bf16 v[24:27], v[166:169], v[206:209], v[24:27]
	v_mfma_f32_16x16x32_bf16 v[12:15], v[158:161], v[214:217], v[12:15]
	v_mfma_f32_16x16x32_bf16 v[8:11], v[166:169], v[214:217], v[8:11]
	s_setprio 0
	s_setprio 1
	v_mfma_f32_16x16x32_bf16 v[52:55], v[170:173], v[186:189], v[52:55]
	v_mfma_f32_16x16x32_bf16 v[48:51], v[178:181], v[186:189], v[48:51]
	v_mfma_f32_16x16x32_bf16 v[36:39], v[170:173], v[194:197], v[36:39]
	v_mfma_f32_16x16x32_bf16 v[32:35], v[178:181], v[194:197], v[32:35]
	v_mfma_f32_16x16x32_bf16 v[20:23], v[170:173], v[202:205], v[20:23]
	v_mfma_f32_16x16x32_bf16 v[16:19], v[178:181], v[202:205], v[16:19]
	v_mfma_f32_16x16x32_bf16 v[4:7], v[170:173], v[210:213], v[4:7]
	v_mfma_f32_16x16x32_bf16 v[0:3], v[178:181], v[210:213], v[0:3]
	v_mfma_f32_16x16x32_bf16 v[52:55], v[174:177], v[190:193], v[52:55]
	v_mfma_f32_16x16x32_bf16 v[48:51], v[182:185], v[190:193], v[48:51]
	v_mfma_f32_16x16x32_bf16 v[36:39], v[174:177], v[198:201], v[36:39]
	v_mfma_f32_16x16x32_bf16 v[32:35], v[182:185], v[198:201], v[32:35]
	v_mfma_f32_16x16x32_bf16 v[20:23], v[174:177], v[206:209], v[20:23]
	v_mfma_f32_16x16x32_bf16 v[16:19], v[182:185], v[206:209], v[16:19]
	v_mfma_f32_16x16x32_bf16 v[4:7], v[174:177], v[214:217], v[4:7]
	v_mfma_f32_16x16x32_bf16 v[0:3], v[182:185], v[214:217], v[0:3]
	s_setprio 0
	s_barrier
	s_add_i32 s60, 0, 0x18000
	v_add_u32_e32 v153, s60, v147
	s_add_i32 s61, 0, 0x1c000
	ds_read_b128 v[154:157], v153
	ds_read_b128 v[158:161], v153 offset:1024
	ds_read_b128 v[162:165], v153 offset:2048
	ds_read_b128 v[166:169], v153 offset:3072
	v_add_u32_e32 v153, s61, v147
	ds_read_b128 v[170:173], v153
	ds_read_b128 v[174:177], v153 offset:1024
	ds_read_b128 v[178:181], v153 offset:2048
	ds_read_b128 v[182:185], v153 offset:3072
	s_add_u32 s34, s34, 0x80000
	s_addc_u32 s35, s35, 0
	s_mov_b32 m0, s37
	v_lshl_add_u64 v[224:225], s[34:35], 0, v[128:129]
	ds_read_b128 v[186:189], v151 offset:32768
	ds_read_b128 v[190:193], v151 offset:33792
	ds_read_b128 v[194:197], v151 offset:34816
	ds_read_b128 v[198:201], v151 offset:35840
	ds_read_b128 v[202:205], v151 offset:36864
	ds_read_b128 v[206:209], v151 offset:37888
	ds_read_b128 v[210:213], v151 offset:38912
	ds_read_b128 v[214:217], v151 offset:39936
	global_load_lds_dwordx4 v[224:225], off
	v_lshl_add_u64 v[224:225], s[34:35], 0, v[132:133]
	s_mov_b32 m0, s48
	s_nop 0
	global_load_lds_dwordx4 v[224:225], off
	s_nop 0
	s_nop 0
	s_nop 0
	s_waitcnt vmcnt(8)
	s_waitcnt lgkmcnt(0)
	s_barrier
	s_setprio 1
	s_waitcnt lgkmcnt(0)
	v_mfma_f32_16x16x32_bf16 v[124:127], v[154:157], v[186:189], v[124:127]
	v_mfma_f32_16x16x32_bf16 v[120:123], v[162:165], v[186:189], v[120:123]
	v_mfma_f32_16x16x32_bf16 v[108:111], v[154:157], v[194:197], v[108:111]
	v_mfma_f32_16x16x32_bf16 v[104:107], v[162:165], v[194:197], v[104:107]
	v_mfma_f32_16x16x32_bf16 v[92:95], v[154:157], v[202:205], v[92:95]
	v_mfma_f32_16x16x32_bf16 v[88:91], v[162:165], v[202:205], v[88:91]
	v_mfma_f32_16x16x32_bf16 v[76:79], v[154:157], v[210:213], v[76:79]
	v_mfma_f32_16x16x32_bf16 v[72:75], v[162:165], v[210:213], v[72:75]
	v_mfma_f32_16x16x32_bf16 v[124:127], v[158:161], v[190:193], v[124:127]
	v_mfma_f32_16x16x32_bf16 v[120:123], v[166:169], v[190:193], v[120:123]
	v_mfma_f32_16x16x32_bf16 v[108:111], v[158:161], v[198:201], v[108:111]
	v_mfma_f32_16x16x32_bf16 v[104:107], v[166:169], v[198:201], v[104:107]
	v_mfma_f32_16x16x32_bf16 v[92:95], v[158:161], v[206:209], v[92:95]
	v_mfma_f32_16x16x32_bf16 v[88:91], v[166:169], v[206:209], v[88:91]
	v_mfma_f32_16x16x32_bf16 v[76:79], v[158:161], v[214:217], v[76:79]
	v_mfma_f32_16x16x32_bf16 v[72:75], v[166:169], v[214:217], v[72:75]
	s_setprio 0
	s_setprio 1
	v_mfma_f32_16x16x32_bf16 v[116:119], v[170:173], v[186:189], v[116:119]
	v_mfma_f32_16x16x32_bf16 v[112:115], v[178:181], v[186:189], v[112:115]
	v_mfma_f32_16x16x32_bf16 v[100:103], v[170:173], v[194:197], v[100:103]
	v_mfma_f32_16x16x32_bf16 v[96:99], v[178:181], v[194:197], v[96:99]
	v_mfma_f32_16x16x32_bf16 v[84:87], v[170:173], v[202:205], v[84:87]
	v_mfma_f32_16x16x32_bf16 v[80:83], v[178:181], v[202:205], v[80:83]
	v_mfma_f32_16x16x32_bf16 v[68:71], v[170:173], v[210:213], v[68:71]
	v_mfma_f32_16x16x32_bf16 v[64:67], v[178:181], v[210:213], v[64:67]
	v_mfma_f32_16x16x32_bf16 v[116:119], v[174:177], v[190:193], v[116:119]
	v_mfma_f32_16x16x32_bf16 v[112:115], v[182:185], v[190:193], v[112:115]
	v_mfma_f32_16x16x32_bf16 v[100:103], v[174:177], v[198:201], v[100:103]
	v_mfma_f32_16x16x32_bf16 v[96:99], v[182:185], v[198:201], v[96:99]
	v_mfma_f32_16x16x32_bf16 v[84:87], v[174:177], v[206:209], v[84:87]
	v_mfma_f32_16x16x32_bf16 v[80:83], v[182:185], v[206:209], v[80:83]
	v_mfma_f32_16x16x32_bf16 v[68:71], v[174:177], v[214:217], v[68:71]
	v_mfma_f32_16x16x32_bf16 v[64:67], v[182:185], v[214:217], v[64:67]
	s_setprio 0
	s_barrier
; #define PG8_BAR __builtin_amdgcn_s_barrier()
; template <class Epi, class Sched, bool ALIGN_EPI = false, bool SP2 = false, bool FP8 = false, bool MIX8 = false>
; __device__ __forceinline__ void gemm_phase(PG8_LAS unsigned char* lds, const Gemm g, const Sched& S, const Epi& E) {
;     ...
;         if constexpr (ALIGN_EPI) { if (wr == 0) PG8_BAR; }
	s_add_i32 s34, s60, s46
	v_lshl_add_u64 v[144:145], v[144:145], 0, s[14:15]
	s_mov_b32 m0, s34
	ds_read_b128 v[186:189], v151 offset:49152
	ds_read_b128 v[190:193], v151 offset:50176
	ds_read_b128 v[194:197], v151 offset:51200
	ds_read_b128 v[198:201], v151 offset:52224
	ds_read_b128 v[202:205], v151 offset:53248
	ds_read_b128 v[206:209], v151 offset:54272
	ds_read_b128 v[210:213], v151 offset:55296
	ds_read_b128 v[214:217], v151 offset:56320
	global_load_lds_dwordx4 v[144:145], off
	s_add_i32 m0, s34, 0x2000
	s_add_u32 s30, s30, 0x80080
	v_lshl_add_u64 v[144:145], v[218:219], 0, s[14:15]
	s_addc_u32 s31, s31, 0
	s_add_i32 s34, s61, s46
	global_load_lds_dwordx4 v[144:145], off
	v_lshl_add_u64 v[144:145], s[30:31], 0, v[130:131]
	s_mov_b32 m0, s34
	s_nop 0
	global_load_lds_dwordx4 v[144:145], off
	v_lshl_add_u64 v[144:145], s[30:31], 0, v[134:135]
	s_add_i32 m0, s34, 0x2000
	s_nop 0
	global_load_lds_dwordx4 v[144:145], off
	v_lshl_add_u64 v[144:145], v[220:221], 0, s[14:15]
	s_mov_b32 m0, s50
	s_nop 0
	global_load_lds_dwordx4 v[144:145], off
	v_lshl_add_u64 v[144:145], v[222:223], 0, s[14:15]
	s_mov_b32 m0, s51
	s_nop 0
	global_load_lds_dwordx4 v[144:145], off
	s_nop 0
	s_nop 0
	s_nop 0
	s_nop 0
	s_nop 0
	s_nop 0
	s_nop 0
	s_nop 0
	s_nop 0
	s_nop 0
	s_nop 0
	s_nop 0
	s_nop 0
	s_nop 0
	s_waitcnt vmcnt(8)
	s_waitcnt lgkmcnt(0)
	s_barrier
	s_setprio 1
	s_waitcnt lgkmcnt(0)
	v_mfma_f32_16x16x32_bf16 v[60:63], v[154:157], v[186:189], v[60:63]
	v_mfma_f32_16x16x32_bf16 v[56:59], v[162:165], v[186:189], v[56:59]
	v_mfma_f32_16x16x32_bf16 v[44:47], v[154:157], v[194:197], v[44:47]
	v_mfma_f32_16x16x32_bf16 v[40:43], v[162:165], v[194:197], v[40:43]
	v_mfma_f32_16x16x32_bf16 v[28:31], v[154:157], v[202:205], v[28:31]
	v_mfma_f32_16x16x32_bf16 v[24:27], v[162:165], v[202:205], v[24:27]
	v_mfma_f32_16x16x32_bf16 v[12:15], v[154:157], v[210:213], v[12:15]
	v_mfma_f32_16x16x32_bf16 v[8:11], v[162:165], v[210:213], v[8:11]
	v_mfma_f32_16x16x32_bf16 v[60:63], v[158:161], v[190:193], v[60:63]
	v_mfma_f32_16x16x32_bf16 v[56:59], v[166:169], v[190:193], v[56:59]
	v_mfma_f32_16x16x32_bf16 v[44:47], v[158:161], v[198:201], v[44:47]
	v_mfma_f32_16x16x32_bf16 v[40:43], v[166:169], v[198:201], v[40:43]
	v_mfma_f32_16x16x32_bf16 v[28:31], v[158:161], v[206:209], v[28:31]
	v_mfma_f32_16x16x32_bf16 v[24:27], v[166:169], v[206:209], v[24:27]
	v_mfma_f32_16x16x32_bf16 v[12:15], v[158:161], v[214:217], v[12:15]
	v_mfma_f32_16x16x32_bf16 v[8:11], v[166:169], v[214:217], v[8:11]
	s_setprio 0
	s_setprio 1
	v_mfma_f32_16x16x32_bf16 v[52:55], v[170:173], v[186:189], v[52:55]
	v_mfma_f32_16x16x32_bf16 v[48:51], v[178:181], v[186:189], v[48:51]
	v_mfma_f32_16x16x32_bf16 v[36:39], v[170:173], v[194:197], v[36:39]
	v_mfma_f32_16x16x32_bf16 v[32:35], v[178:181], v[194:197], v[32:35]
	v_mfma_f32_16x16x32_bf16 v[20:23], v[170:173], v[202:205], v[20:23]
	v_mfma_f32_16x16x32_bf16 v[16:19], v[178:181], v[202:205], v[16:19]
	v_mfma_f32_16x16x32_bf16 v[4:7], v[170:173], v[210:213], v[4:7]
	v_mfma_f32_16x16x32_bf16 v[0:3], v[178:181], v[210:213], v[0:3]
	v_mfma_f32_16x16x32_bf16 v[52:55], v[174:177], v[190:193], v[52:55]
	v_mfma_f32_16x16x32_bf16 v[48:51], v[182:185], v[190:193], v[48:51]
	v_mfma_f32_16x16x32_bf16 v[36:39], v[174:177], v[198:201], v[36:39]
	v_mfma_f32_16x16x32_bf16 v[32:35], v[182:185], v[198:201], v[32:35]
	v_mfma_f32_16x16x32_bf16 v[20:23], v[174:177], v[206:209], v[20:23]
	v_mfma_f32_16x16x32_bf16 v[16:19], v[182:185], v[206:209], v[16:19]
	v_mfma_f32_16x16x32_bf16 v[4:7], v[174:177], v[214:217], v[4:7]
	v_mfma_f32_16x16x32_bf16 v[0:3], v[182:185], v[214:217], v[0:3]
	s_setprio 0
	s_barrier
	s_add_i32 s59, s59, 2
	s_add_u32 s28, s28, 0x100
	s_addc_u32 s29, s29, 0
	s_add_u32 s27, s27, 0x100
	s_addc_u32 s33, s33, 0
	s_cmp_gt_u32 s59, 29
	s_cbranch_scc0 .LBB0_723
	s_and_b64 vcc, exec, s[16:17]
	s_cbranch_vccz .LBB0_726
	s_barrier
